# S5 input U stored group-major by the in-projection epilogue (contiguous 64 KB per S5 item) on top of fragment-order Win/MW
# speedup vs baseline: 1.0023x; 1.0023x over previous
; __device__ __forceinline__ float fgelu(float x) { return x * fsigmoid(1.5957691216057308f * (x + 0.044715f * x * x * x)); }
; __device__ __forceinline__ u32x4 pack8(const f32x4 a, const f32x4 b) { u32x4 w; w.x = cvt_pk_bf16(a[0], a[1]); w.y = cvt_pk_bf16(a[2], a[3]); w.z = cvt_pk_bf16(b[0], b[1]); w.w = cvt_pk_bf16(b[2], b[3]); return w; }
;     __device__ __forceinline__ void operator()(const Acc& acc, const Unit& u, int wr, int wc, int fr, int fq) const {
;         int row0 = u.pm * BM + wr * 64 + fr, col0 = (u.pn & 3) * BM + wc * 32 + 8 * fq; const int seg = u.pn >> 2; asm volatile("" : "+v"(row0), "+v"(col0));
;         float sq[2][4];
; #pragma unroll
;         for (int ai = 0; ai < 2; ++ai)
; #pragma unroll
;             for (int m = 0; m < 4; ++m) sq[ai][m] = ssq[row0 + ai * HALF + m * 16];
;         asm volatile("" ::: "memory");
; #pragma unroll
;         for (int ai = 0; ai < 2; ++ai)
; #pragma unroll
;             for (int m = 0; m < 4; ++m) {
;                 const int row = row0 + ai * HALF + m * 16;
;                 const float r = rsqrtf(sq[ai][m] * (1.0f / D) + EPS);
; #pragma unroll
;                 for (int bj = 0; bj < 2; ++bj) {
;                     const size_t o = (size_t)row * DH + col0 + bj * HALF;
;                     f32x4 v0 = acc[ai][bj][m][0] * r, v1 = acc[ai][bj][m][1] * r;
;                     if (seg == 0) { *(u32x4*)(U + o) = pack8(v0, v1); }
;                     else if (seg == 1) { *(f32x4*)(XL + o) = v0; *(f32x4*)(XL + o + 4) = v1; }
;                     else {
; #pragma unroll
;                         for (int j = 0; j < 4; ++j) { v0[j] = fgelu(v0[j]); v1[j] = fgelu(v1[j]); }
;                         *(u32x4*)(GG + o) = pack8(v0, v1);
;                     }
;                 }
;             }
;     }
.LBB0_367:
	s_cmp_eq_u32 s4, 32
	s_cselect_b64 s[98:99], -1, 0
	v_lshl_add_u32 v132, s4, 8, v144
	s_lshl_b32 s4, s17, 8
	s_and_b32 s4, s4, 0x300
	v_or_b32_e32 v134, s4, v147
	s_cmp_gt_u32 s17, 3
	v_ashrrev_i32_e32 v133, 31, v132
	v_lshl_add_u64 v[136:137], v[132:133], 2, s[50:51]
	global_load_dword v138, v[136:137], off
	global_load_dword v156, v[136:137], off offset:64
	global_load_dword v155, v[136:137], off offset:128
	global_load_dword v154, v[136:137], off offset:192
	global_load_dword v153, v[136:137], off offset:512
	global_load_dword v152, v[136:137], off offset:576
	global_load_dword v151, v[136:137], off offset:640
	global_load_dword v150, v[136:137], off offset:704
	s_cselect_b64 s[4:5], -1, 0
	s_and_b32 s6, s17, -4
	s_cmp_lg_u32 s6, 4
	s_cselect_b64 s[6:7], -1, 0
	v_ashrrev_i32_e32 v135, 31, v134
	s_mov_b64 s[8:9], -1
	s_waitcnt vmcnt(7)
	v_fmamk_f32 v136, v138, 0x3a000000, v149
	v_cmp_gt_f32_e32 vcc, s29, v136
	v_mul_f32_e32 v137, 0x4b800000, v136
	v_lshlrev_b64 v[138:139], 10, v[132:133]
	v_cndmask_b32_e32 v136, v136, v137, vcc
	v_rsq_f32_e32 v136, v136
	v_lshl_add_u64 v[138:139], v[138:139], 0, v[134:135]
	v_mul_f32_e32 v137, 0x45800000, v136
	v_cndmask_b32_e32 v136, v136, v137, vcc
	v_pk_mul_f32 v[128:129], v[128:129], v[136:137] op_sel_hi:[1,0]
	v_pk_mul_f32 v[126:127], v[126:127], v[136:137] op_sel_hi:[1,0]
	v_pk_mul_f32 v[124:125], v[124:125], v[136:137] op_sel_hi:[1,0]
	v_pk_mul_f32 v[122:123], v[122:123], v[136:137] op_sel_hi:[1,0]
	v_cndmask_b32_e64 v137, 0, 1, s[6:7]
	s_and_b64 vcc, exec, s[4:5]
	v_cmp_ne_u32_e64 s[6:7], 1, v137
	s_cbranch_vccz .LBB0_373
	s_and_b64 vcc, exec, s[6:7]
	s_cbranch_vccnz .LBB0_370
	v_mul_f32_e32 v159, 0x3d372713, v123
	v_mul_f32_e32 v159, v123, v159
	v_fma_f32 v159, v123, v159, v123
	v_mul_f32_e32 v159, 0x3fcc422a, v159
	v_mul_f32_e32 v159, 0xbfb8aa3b, v159
	v_exp_f32_e32 v159, v159
	v_mul_f32_e32 v160, 0x3d372713, v128
	v_mul_f32_e32 v161, 0x3d372713, v124
	v_mul_f32_e32 v160, v128, v160
	v_mul_f32_e32 v161, v124, v161
	v_fma_f32 v160, v128, v160, v128
	v_fma_f32 v161, v124, v161, v124
	v_mul_f32_e32 v160, 0x3fcc422a, v160
	v_mul_f32_e32 v161, 0x3fcc422a, v161
	v_add_f32_e32 v159, 1.0, v159
	v_mul_f32_e32 v160, 0xbfb8aa3b, v160
	v_mul_f32_e32 v161, 0xbfb8aa3b, v161
	v_rcp_f32_e32 v159, v159
	v_exp_f32_e32 v160, v160
	v_exp_f32_e32 v161, v161
	v_mul_f32_e32 v157, 0x3d372713, v122
	v_mul_f32_e32 v162, v123, v159
	v_add_f32_e32 v159, 1.0, v160
	v_add_f32_e32 v160, 1.0, v161
	v_mul_f32_e32 v161, 0x3d372713, v129
	v_mul_f32_e32 v158, 0x3d372713, v127
	v_mul_f32_e32 v161, v129, v161
	v_mul_f32_e32 v163, 0x3d372713, v125
	v_mul_f32_e32 v137, 0x3d372713, v126
	v_mul_f32_e32 v157, v122, v157
	v_mul_f32_e32 v158, v127, v158
	v_fma_f32 v161, v129, v161, v129
	v_mul_f32_e32 v163, v125, v163
	v_mul_f32_e32 v137, v126, v137
	v_fma_f32 v157, v122, v157, v122
	v_fma_f32 v158, v127, v158, v127
	v_mul_f32_e32 v161, 0x3fcc422a, v161
	v_fma_f32 v163, v125, v163, v125
	v_fma_f32 v137, v126, v137, v126
	v_mul_f32_e32 v157, 0x3fcc422a, v157
	v_mul_f32_e32 v158, 0x3fcc422a, v158
	v_mul_f32_e32 v161, 0xbfb8aa3b, v161
	v_mul_f32_e32 v163, 0x3fcc422a, v163
	v_mul_f32_e32 v137, 0x3fcc422a, v137
	v_mul_f32_e32 v157, 0xbfb8aa3b, v157
	v_mul_f32_e32 v158, 0xbfb8aa3b, v158
	v_exp_f32_e32 v161, v161
	v_mul_f32_e32 v163, 0xbfb8aa3b, v163
	v_mul_f32_e32 v137, 0xbfb8aa3b, v137
	v_exp_f32_e32 v157, v157
	v_exp_f32_e32 v158, v158
	v_exp_f32_e32 v163, v163
	v_exp_f32_e32 v137, v137
	v_add_f32_e32 v161, 1.0, v161
	v_add_f32_e32 v157, 1.0, v157
	v_add_f32_e32 v158, 1.0, v158
	v_rcp_f32_e32 v159, v159
	v_rcp_f32_e32 v160, v160
	v_rcp_f32_e32 v161, v161
	v_add_f32_e32 v163, 1.0, v163
	v_add_f32_e32 v137, 1.0, v137
	v_rcp_f32_e32 v157, v157
	v_rcp_f32_e32 v158, v158
	v_rcp_f32_e32 v163, v163
	v_rcp_f32_e32 v137, v137
	v_readlane_b32 s8, v254, 63
	v_mul_f32_e32 v159, v128, v159
	v_mul_f32_e32 v164, v124, v160
	v_mul_f32_e32 v160, v129, v161
	v_readlane_b32 s9, v253, 0
	v_mul_f32_e32 v157, v122, v157
	v_mul_f32_e32 v158, v127, v158
	v_mul_f32_e32 v161, v125, v163
	v_cvt_pk_bf16_f32 v159, v159, v160
	v_cvt_pk_bf16_f32 v160, v157, v162
	v_lshl_add_u64 v[162:163], v[138:139], 1, s[8:9]
	s_mov_b64 s[8:9], 0
	v_mul_f32_e32 v137, v126, v137
	v_cvt_pk_bf16_f32 v158, v137, v158
	v_cvt_pk_bf16_f32 v161, v164, v161
	global_store_dwordx4 v[162:163], v[158:161], off

; __device__ __forceinline__ u32x4 pack8(const f32x4 a, const f32x4 b) { u32x4 w; w.x = cvt_pk_bf16(a[0], a[1]); w.y = cvt_pk_bf16(a[2], a[3]); w.z = cvt_pk_bf16(b[0], b[1]); w.w = cvt_pk_bf16(b[2], b[3]); return w; }
;     __device__ __forceinline__ void operator()(const Acc& acc, const Unit& u, int wr, int wc, int fr, int fq) const {
;     ...
;                     const size_t o = (size_t)row * DH + col0 + bj * HALF;
;                     f32x4 v0 = acc[ai][bj][m][0] * r, v1 = acc[ai][bj][m][1] * r;
;                     if (seg == 0) { *(u32x4*)(U + o) = pack8(v0, v1); }
.LBB0_373:
	s_andn2_b64 vcc, exec, s[8:9]
	s_cbranch_vccnz .LBB0_375
	v_readlane_b32 s8, v254, 40
	v_readlane_b32 s9, v254, 41
	v_cvt_pk_bf16_f32 v126, v126, v127
	v_cvt_pk_bf16_f32 v127, v128, v129
	v_cvt_pk_bf16_f32 v128, v122, v123
	v_cvt_pk_bf16_f32 v129, v124, v125
	s_nop 1
	v_bfe_u32 v122, v138, 4, 6
	v_bfe_u32 v123, v138, 10, 11
	v_lshl_or_b32 v122, v122, 11, v123
	v_bfe_u32 v123, v138, 3, 1
	v_lshl_or_b32 v122, v122, 1, v123
	v_lshrrev_b32_e32 v123, 21, v138
	v_lshl_or_b32 v122, v123, 18, v122
	v_lshlrev_b32_e32 v122, 4, v122
	v_lshlrev_b32_e32 v123, 1, v138
	v_cndmask_b32_e64 v122, v122, v123, s[98:99]
	global_store_dwordx4 v122, v[126:129], s[8:9]

; __device__ __forceinline__ u32x4 pack8(const f32x4 a, const f32x4 b) { u32x4 w; w.x = cvt_pk_bf16(a[0], a[1]); w.y = cvt_pk_bf16(a[2], a[3]); w.z = cvt_pk_bf16(b[0], b[1]); w.w = cvt_pk_bf16(b[2], b[3]); return w; }
;     __device__ __forceinline__ void operator()(const Acc& acc, const Unit& u, int wr, int wc, int fr, int fq) const {
;     ...
;                     const size_t o = (size_t)row * DH + col0 + bj * HALF;
;                     f32x4 v0 = acc[ai][bj][m][0] * r, v1 = acc[ai][bj][m][1] * r;
;                     if (seg == 0) { *(u32x4*)(U + o) = pack8(v0, v1); }
.LBB0_381:
	s_andn2_b64 vcc, exec, s[4:5]
	s_cbranch_vccnz .LBB0_383
	v_readlane_b32 s4, v254, 40
	v_readlane_b32 s5, v254, 41
	v_cvt_pk_bf16_f32 v118, v118, v119
	v_cvt_pk_bf16_f32 v119, v120, v121
	v_cvt_pk_bf16_f32 v120, v114, v115
	v_cvt_pk_bf16_f32 v121, v116, v117
	s_nop 1
	v_bfe_u32 v114, v122, 4, 6
	v_bfe_u32 v115, v122, 10, 11
	v_lshl_or_b32 v114, v114, 11, v115
	v_bfe_u32 v115, v122, 3, 1
	v_lshl_or_b32 v114, v114, 1, v115
	v_lshrrev_b32_e32 v115, 21, v122
	v_lshl_or_b32 v114, v115, 18, v114
	v_lshlrev_b32_e32 v114, 4, v114
	v_lshlrev_b32_e32 v115, 1, v122
	v_cndmask_b32_e64 v114, v114, v115, s[98:99]
	global_store_dwordx4 v114, v[118:121], s[4:5]

; __device__ __forceinline__ u32x4 pack8(const f32x4 a, const f32x4 b) { u32x4 w; w.x = cvt_pk_bf16(a[0], a[1]); w.y = cvt_pk_bf16(a[2], a[3]); w.z = cvt_pk_bf16(b[0], b[1]); w.w = cvt_pk_bf16(b[2], b[3]); return w; }
;     __device__ __forceinline__ void operator()(const Acc& acc, const Unit& u, int wr, int wc, int fr, int fq) const {
;     ...
;                     const size_t o = (size_t)row * DH + col0 + bj * HALF;
;                     f32x4 v0 = acc[ai][bj][m][0] * r, v1 = acc[ai][bj][m][1] * r;
;                     if (seg == 0) { *(u32x4*)(U + o) = pack8(v0, v1); }
.LBB0_389:
	s_andn2_b64 vcc, exec, s[4:5]
	s_cbranch_vccnz .LBB0_391
	v_readlane_b32 s4, v254, 40
	v_readlane_b32 s5, v254, 41
	v_cvt_pk_bf16_f32 v110, v110, v111
	v_cvt_pk_bf16_f32 v111, v112, v113
	v_cvt_pk_bf16_f32 v112, v106, v107
	v_cvt_pk_bf16_f32 v113, v108, v109
	s_nop 1
	v_bfe_u32 v106, v116, 4, 6
	v_bfe_u32 v107, v116, 10, 11
	v_lshl_or_b32 v106, v106, 11, v107
	v_bfe_u32 v107, v116, 3, 1
	v_lshl_or_b32 v106, v106, 1, v107
	v_lshrrev_b32_e32 v107, 21, v116
	v_lshl_or_b32 v106, v107, 18, v106
	v_lshlrev_b32_e32 v106, 4, v106
	v_lshlrev_b32_e32 v107, 1, v116
	v_cndmask_b32_e64 v106, v106, v107, s[98:99]
	global_store_dwordx4 v106, v[110:113], s[4:5]

; __device__ __forceinline__ u32x4 pack8(const f32x4 a, const f32x4 b) { u32x4 w; w.x = cvt_pk_bf16(a[0], a[1]); w.y = cvt_pk_bf16(a[2], a[3]); w.z = cvt_pk_bf16(b[0], b[1]); w.w = cvt_pk_bf16(b[2], b[3]); return w; }
;     __device__ __forceinline__ void operator()(const Acc& acc, const Unit& u, int wr, int wc, int fr, int fq) const {
;     ...
;                     const size_t o = (size_t)row * DH + col0 + bj * HALF;
;                     f32x4 v0 = acc[ai][bj][m][0] * r, v1 = acc[ai][bj][m][1] * r;
;                     if (seg == 0) { *(u32x4*)(U + o) = pack8(v0, v1); }
.LBB0_397:
	s_andn2_b64 vcc, exec, s[4:5]
	s_cbranch_vccnz .LBB0_399
	v_readlane_b32 s4, v254, 40
	v_readlane_b32 s5, v254, 41
	v_cvt_pk_bf16_f32 v102, v102, v103
	v_cvt_pk_bf16_f32 v103, v104, v105
	v_cvt_pk_bf16_f32 v104, v98, v99
	v_cvt_pk_bf16_f32 v105, v100, v101
	s_nop 1
	v_bfe_u32 v98, v106, 4, 6
	v_bfe_u32 v99, v106, 10, 11
	v_lshl_or_b32 v98, v98, 11, v99
	v_bfe_u32 v99, v106, 3, 1
	v_lshl_or_b32 v98, v98, 1, v99
	v_lshrrev_b32_e32 v99, 21, v106
	v_lshl_or_b32 v98, v99, 18, v98
	v_lshlrev_b32_e32 v98, 4, v98
	v_lshlrev_b32_e32 v99, 1, v106
	v_cndmask_b32_e64 v98, v98, v99, s[98:99]
	global_store_dwordx4 v98, v[102:105], s[4:5]

; __device__ __forceinline__ u32x4 pack8(const f32x4 a, const f32x4 b) { u32x4 w; w.x = cvt_pk_bf16(a[0], a[1]); w.y = cvt_pk_bf16(a[2], a[3]); w.z = cvt_pk_bf16(b[0], b[1]); w.w = cvt_pk_bf16(b[2], b[3]); return w; }
;     __device__ __forceinline__ void operator()(const Acc& acc, const Unit& u, int wr, int wc, int fr, int fq) const {
;     ...
; #pragma unroll
;                 for (int bj = 0; bj < 2; ++bj) {
;                     const size_t o = (size_t)row * DH + col0 + bj * HALF;
;                     f32x4 v0 = acc[ai][bj][m][0] * r, v1 = acc[ai][bj][m][1] * r;
;                     if (seg == 0) { *(u32x4*)(U + o) = pack8(v0, v1); }
.LBB0_405:
	s_andn2_b64 vcc, exec, s[4:5]
	s_cbranch_vccnz .LBB0_407
	v_readlane_b32 s4, v254, 40
	v_readlane_b32 s5, v254, 41
	v_cvt_pk_bf16_f32 v94, v94, v95
	v_cvt_pk_bf16_f32 v95, v96, v97
	v_cvt_pk_bf16_f32 v96, v90, v91
	v_cvt_pk_bf16_f32 v97, v92, v93
	s_nop 1
	v_bfe_u32 v90, v100, 4, 6
	v_bfe_u32 v91, v100, 10, 11
	v_lshl_or_b32 v90, v90, 11, v91
	v_bfe_u32 v91, v100, 3, 1
	v_lshl_or_b32 v90, v90, 1, v91
	v_lshrrev_b32_e32 v91, 21, v100
	v_lshl_or_b32 v90, v91, 18, v90
	v_lshlrev_b32_e32 v90, 4, v90
	v_lshlrev_b32_e32 v91, 1, v100
	v_cndmask_b32_e64 v90, v90, v91, s[98:99]
	global_store_dwordx4 v90, v[94:97], s[4:5]

; __device__ __forceinline__ u32x4 pack8(const f32x4 a, const f32x4 b) { u32x4 w; w.x = cvt_pk_bf16(a[0], a[1]); w.y = cvt_pk_bf16(a[2], a[3]); w.z = cvt_pk_bf16(b[0], b[1]); w.w = cvt_pk_bf16(b[2], b[3]); return w; }
;     __device__ __forceinline__ void operator()(const Acc& acc, const Unit& u, int wr, int wc, int fr, int fq) const {
;     ...
; #pragma unroll
;                 for (int bj = 0; bj < 2; ++bj) {
;                     const size_t o = (size_t)row * DH + col0 + bj * HALF;
;                     f32x4 v0 = acc[ai][bj][m][0] * r, v1 = acc[ai][bj][m][1] * r;
;                     if (seg == 0) { *(u32x4*)(U + o) = pack8(v0, v1); }
.LBB0_413:
	s_andn2_b64 vcc, exec, s[4:5]
	s_cbranch_vccnz .LBB0_415
	v_readlane_b32 s4, v254, 40
	v_readlane_b32 s5, v254, 41
	v_cvt_pk_bf16_f32 v86, v86, v87
	v_cvt_pk_bf16_f32 v87, v88, v89
	v_cvt_pk_bf16_f32 v88, v82, v83
	v_cvt_pk_bf16_f32 v89, v84, v85
	s_nop 1
	v_bfe_u32 v82, v90, 4, 6
	v_bfe_u32 v83, v90, 10, 11
	v_lshl_or_b32 v82, v82, 11, v83
	v_bfe_u32 v83, v90, 3, 1
	v_lshl_or_b32 v82, v82, 1, v83
	v_lshrrev_b32_e32 v83, 21, v90
	v_lshl_or_b32 v82, v83, 18, v82
	v_lshlrev_b32_e32 v82, 4, v82
	v_lshlrev_b32_e32 v83, 1, v90
	v_cndmask_b32_e64 v82, v82, v83, s[98:99]
	global_store_dwordx4 v82, v[86:89], s[4:5]

; __device__ __forceinline__ u32x4 pack8(const f32x4 a, const f32x4 b) { u32x4 w; w.x = cvt_pk_bf16(a[0], a[1]); w.y = cvt_pk_bf16(a[2], a[3]); w.z = cvt_pk_bf16(b[0], b[1]); w.w = cvt_pk_bf16(b[2], b[3]); return w; }
;     __device__ __forceinline__ void operator()(const Acc& acc, const Unit& u, int wr, int wc, int fr, int fq) const {
;     ...
; #pragma unroll
;                 for (int bj = 0; bj < 2; ++bj) {
;                     const size_t o = (size_t)row * DH + col0 + bj * HALF;
;                     f32x4 v0 = acc[ai][bj][m][0] * r, v1 = acc[ai][bj][m][1] * r;
;                     if (seg == 0) { *(u32x4*)(U + o) = pack8(v0, v1); }
.LBB0_421:
	s_andn2_b64 vcc, exec, s[4:5]
	s_cbranch_vccnz .LBB0_423
	v_readlane_b32 s4, v254, 40
	v_readlane_b32 s5, v254, 41
	v_cvt_pk_bf16_f32 v70, v70, v71
	v_cvt_pk_bf16_f32 v71, v72, v73
	v_cvt_pk_bf16_f32 v72, v66, v67
	v_cvt_pk_bf16_f32 v73, v68, v69
	s_nop 1
	v_bfe_u32 v66, v84, 4, 6
	v_bfe_u32 v67, v84, 10, 11
	v_lshl_or_b32 v66, v66, 11, v67
	v_bfe_u32 v67, v84, 3, 1
	v_lshl_or_b32 v66, v66, 1, v67
	v_lshrrev_b32_e32 v67, 21, v84
	v_lshl_or_b32 v66, v67, 18, v66
	v_lshlrev_b32_e32 v66, 4, v66
	v_lshlrev_b32_e32 v67, 1, v84
	v_cndmask_b32_e64 v66, v66, v67, s[98:99]
	global_store_dwordx4 v66, v[70:73], s[4:5]

; __device__ __forceinline__ u32x4 pack8(const f32x4 a, const f32x4 b) { u32x4 w; w.x = cvt_pk_bf16(a[0], a[1]); w.y = cvt_pk_bf16(a[2], a[3]); w.z = cvt_pk_bf16(b[0], b[1]); w.w = cvt_pk_bf16(b[2], b[3]); return w; }
;     __device__ __forceinline__ void operator()(const Acc& acc, const Unit& u, int wr, int wc, int fr, int fq) const {
;     ...
; #pragma unroll
;                 for (int bj = 0; bj < 2; ++bj) {
;                     const size_t o = (size_t)row * DH + col0 + bj * HALF;
;                     f32x4 v0 = acc[ai][bj][m][0] * r, v1 = acc[ai][bj][m][1] * r;
;                     if (seg == 0) { *(u32x4*)(U + o) = pack8(v0, v1); }
.LBB0_429:
	s_andn2_b64 vcc, exec, s[4:5]
	s_cbranch_vccnz .LBB0_431
	v_readlane_b32 s4, v254, 40
	v_readlane_b32 s5, v254, 41
	v_cvt_pk_bf16_f32 v54, v54, v55
	v_cvt_pk_bf16_f32 v55, v56, v57
	v_cvt_pk_bf16_f32 v56, v50, v51
	v_cvt_pk_bf16_f32 v57, v52, v53
	s_nop 1
	v_bfe_u32 v50, v66, 4, 6
	v_bfe_u32 v51, v66, 10, 11
	v_lshl_or_b32 v50, v50, 11, v51
	v_bfe_u32 v51, v66, 3, 1
	v_lshl_or_b32 v50, v50, 1, v51
	v_lshrrev_b32_e32 v51, 21, v66
	v_lshl_or_b32 v50, v51, 18, v50
	v_lshlrev_b32_e32 v50, 4, v50
	v_lshlrev_b32_e32 v51, 1, v66
	v_cndmask_b32_e64 v50, v50, v51, s[98:99]
	global_store_dwordx4 v50, v[54:57], s[4:5]

; __device__ __forceinline__ u32x4 pack8(const f32x4 a, const f32x4 b) { u32x4 w; w.x = cvt_pk_bf16(a[0], a[1]); w.y = cvt_pk_bf16(a[2], a[3]); w.z = cvt_pk_bf16(b[0], b[1]); w.w = cvt_pk_bf16(b[2], b[3]); return w; }
;     __device__ __forceinline__ void operator()(const Acc& acc, const Unit& u, int wr, int wc, int fr, int fq) const {
;     ...
; #pragma unroll
;                 for (int bj = 0; bj < 2; ++bj) {
;                     const size_t o = (size_t)row * DH + col0 + bj * HALF;
;                     f32x4 v0 = acc[ai][bj][m][0] * r, v1 = acc[ai][bj][m][1] * r;
;                     if (seg == 0) { *(u32x4*)(U + o) = pack8(v0, v1); }
.LBB0_437:
	s_andn2_b64 vcc, exec, s[4:5]
	s_cbranch_vccnz .LBB0_439
	v_readlane_b32 s4, v254, 40
	v_readlane_b32 s5, v254, 41
	v_cvt_pk_bf16_f32 v50, v50, v51
	v_cvt_pk_bf16_f32 v51, v52, v53
	v_cvt_pk_bf16_f32 v52, v54, v55
	v_cvt_pk_bf16_f32 v53, v56, v57
	s_nop 1
	v_bfe_u32 v54, v68, 4, 6
	v_bfe_u32 v55, v68, 10, 11
	v_lshl_or_b32 v54, v54, 11, v55
	v_bfe_u32 v55, v68, 3, 1
	v_lshl_or_b32 v54, v54, 1, v55
	v_lshrrev_b32_e32 v55, 21, v68
	v_lshl_or_b32 v54, v55, 18, v54
	v_lshlrev_b32_e32 v54, 4, v54
	v_lshlrev_b32_e32 v55, 1, v68
	v_cndmask_b32_e64 v54, v54, v55, s[98:99]
	global_store_dwordx4 v54, v[50:53], s[4:5]

; __device__ __forceinline__ u32x4 pack8(const f32x4 a, const f32x4 b) { u32x4 w; w.x = cvt_pk_bf16(a[0], a[1]); w.y = cvt_pk_bf16(a[2], a[3]); w.z = cvt_pk_bf16(b[0], b[1]); w.w = cvt_pk_bf16(b[2], b[3]); return w; }
;     __device__ __forceinline__ void operator()(const Acc& acc, const Unit& u, int wr, int wc, int fr, int fq) const {
;     ...
; #pragma unroll
;                 for (int bj = 0; bj < 2; ++bj) {
;                     const size_t o = (size_t)row * DH + col0 + bj * HALF;
;                     f32x4 v0 = acc[ai][bj][m][0] * r, v1 = acc[ai][bj][m][1] * r;
;                     if (seg == 0) { *(u32x4*)(U + o) = pack8(v0, v1); }
.LBB0_453:
	s_andn2_b64 vcc, exec, s[4:5]
	s_cbranch_vccnz .LBB0_455
	v_readlane_b32 s4, v254, 40
	v_readlane_b32 s5, v254, 41
	v_cvt_pk_bf16_f32 v46, v46, v47
	v_cvt_pk_bf16_f32 v47, v48, v49
	v_cvt_pk_bf16_f32 v48, v42, v43
	v_cvt_pk_bf16_f32 v49, v44, v45
	s_nop 1
	v_bfe_u32 v42, v52, 4, 6
	v_bfe_u32 v43, v52, 10, 11
	v_lshl_or_b32 v42, v42, 11, v43
	v_bfe_u32 v43, v52, 3, 1
	v_lshl_or_b32 v42, v42, 1, v43
	v_lshrrev_b32_e32 v43, 21, v52
	v_lshl_or_b32 v42, v43, 18, v42
	v_lshlrev_b32_e32 v42, 4, v42
	v_lshlrev_b32_e32 v43, 1, v52
	v_cndmask_b32_e64 v42, v42, v43, s[98:99]
	global_store_dwordx4 v42, v[46:49], s[4:5]

; __device__ __forceinline__ u32x4 pack8(const f32x4 a, const f32x4 b) { u32x4 w; w.x = cvt_pk_bf16(a[0], a[1]); w.y = cvt_pk_bf16(a[2], a[3]); w.z = cvt_pk_bf16(b[0], b[1]); w.w = cvt_pk_bf16(b[2], b[3]); return w; }
;     __device__ __forceinline__ void operator()(const Acc& acc, const Unit& u, int wr, int wc, int fr, int fq) const {
;     ...
; #pragma unroll
;                 for (int bj = 0; bj < 2; ++bj) {
;                     const size_t o = (size_t)row * DH + col0 + bj * HALF;
;                     f32x4 v0 = acc[ai][bj][m][0] * r, v1 = acc[ai][bj][m][1] * r;
;                     if (seg == 0) { *(u32x4*)(U + o) = pack8(v0, v1); }
.LBB0_461:
	s_andn2_b64 vcc, exec, s[4:5]
	s_cbranch_vccnz .LBB0_463
	v_readlane_b32 s4, v254, 40
	v_readlane_b32 s5, v254, 41
	v_cvt_pk_bf16_f32 v38, v38, v39
	v_cvt_pk_bf16_f32 v39, v40, v41
	v_cvt_pk_bf16_f32 v40, v34, v35
	v_cvt_pk_bf16_f32 v41, v36, v37
	s_nop 1
	v_bfe_u32 v34, v42, 4, 6
	v_bfe_u32 v35, v42, 10, 11
	v_lshl_or_b32 v34, v34, 11, v35
	v_bfe_u32 v35, v42, 3, 1
	v_lshl_or_b32 v34, v34, 1, v35
	v_lshrrev_b32_e32 v35, 21, v42
	v_lshl_or_b32 v34, v35, 18, v34
	v_lshlrev_b32_e32 v34, 4, v34
	v_lshlrev_b32_e32 v35, 1, v42
	v_cndmask_b32_e64 v34, v34, v35, s[98:99]
	global_store_dwordx4 v34, v[38:41], s[4:5]

; __device__ __forceinline__ u32x4 pack8(const f32x4 a, const f32x4 b) { u32x4 w; w.x = cvt_pk_bf16(a[0], a[1]); w.y = cvt_pk_bf16(a[2], a[3]); w.z = cvt_pk_bf16(b[0], b[1]); w.w = cvt_pk_bf16(b[2], b[3]); return w; }
;     __device__ __forceinline__ void operator()(const Acc& acc, const Unit& u, int wr, int wc, int fr, int fq) const {
;     ...
; #pragma unroll
;                 for (int bj = 0; bj < 2; ++bj) {
;                     const size_t o = (size_t)row * DH + col0 + bj * HALF;
;                     f32x4 v0 = acc[ai][bj][m][0] * r, v1 = acc[ai][bj][m][1] * r;
;                     if (seg == 0) { *(u32x4*)(U + o) = pack8(v0, v1); }
.LBB0_469:
	s_andn2_b64 vcc, exec, s[4:5]
	s_cbranch_vccnz .LBB0_471
	v_readlane_b32 s4, v254, 40
	v_readlane_b32 s5, v254, 41
	v_cvt_pk_bf16_f32 v30, v30, v31
	v_cvt_pk_bf16_f32 v31, v32, v33
	v_cvt_pk_bf16_f32 v32, v26, v27
	v_cvt_pk_bf16_f32 v33, v28, v29
	s_nop 1
	v_bfe_u32 v26, v36, 4, 6
	v_bfe_u32 v27, v36, 10, 11
	v_lshl_or_b32 v26, v26, 11, v27
	v_bfe_u32 v27, v36, 3, 1
	v_lshl_or_b32 v26, v26, 1, v27
	v_lshrrev_b32_e32 v27, 21, v36
	v_lshl_or_b32 v26, v27, 18, v26
	v_lshlrev_b32_e32 v26, 4, v26
	v_lshlrev_b32_e32 v27, 1, v36
	v_cndmask_b32_e64 v26, v26, v27, s[98:99]
	global_store_dwordx4 v26, v[30:33], s[4:5]

; __device__ __forceinline__ u32x4 pack8(const f32x4 a, const f32x4 b) { u32x4 w; w.x = cvt_pk_bf16(a[0], a[1]); w.y = cvt_pk_bf16(a[2], a[3]); w.z = cvt_pk_bf16(b[0], b[1]); w.w = cvt_pk_bf16(b[2], b[3]); return w; }
;     __device__ __forceinline__ void operator()(const Acc& acc, const Unit& u, int wr, int wc, int fr, int fq) const {
;     ...
; #pragma unroll
;                 for (int bj = 0; bj < 2; ++bj) {
;                     const size_t o = (size_t)row * DH + col0 + bj * HALF;
;                     f32x4 v0 = acc[ai][bj][m][0] * r, v1 = acc[ai][bj][m][1] * r;
;                     if (seg == 0) { *(u32x4*)(U + o) = pack8(v0, v1); }
.LBB0_477:
	s_andn2_b64 vcc, exec, s[4:5]
	s_cbranch_vccnz .LBB0_479
	v_readlane_b32 s4, v254, 40
	v_readlane_b32 s5, v254, 41
	v_cvt_pk_bf16_f32 v22, v22, v23
	v_cvt_pk_bf16_f32 v23, v24, v25
	v_cvt_pk_bf16_f32 v24, v18, v19
	v_cvt_pk_bf16_f32 v25, v20, v21
	s_nop 1
	v_bfe_u32 v18, v26, 4, 6
	v_bfe_u32 v19, v26, 10, 11
	v_lshl_or_b32 v18, v18, 11, v19
	v_bfe_u32 v19, v26, 3, 1
	v_lshl_or_b32 v18, v18, 1, v19
	v_lshrrev_b32_e32 v19, 21, v26
	v_lshl_or_b32 v18, v19, 18, v18
	v_lshlrev_b32_e32 v18, 4, v18
	v_lshlrev_b32_e32 v19, 1, v26
	v_cndmask_b32_e64 v18, v18, v19, s[98:99]
	global_store_dwordx4 v18, v[22:25], s[4:5]

; __device__ __forceinline__ u32x4 pack8(const f32x4 a, const f32x4 b) { u32x4 w; w.x = cvt_pk_bf16(a[0], a[1]); w.y = cvt_pk_bf16(a[2], a[3]); w.z = cvt_pk_bf16(b[0], b[1]); w.w = cvt_pk_bf16(b[2], b[3]); return w; }
;     __device__ __forceinline__ void operator()(const Acc& acc, const Unit& u, int wr, int wc, int fr, int fq) const {
;     ...
; #pragma unroll
;                 for (int bj = 0; bj < 2; ++bj) {
;                     const size_t o = (size_t)row * DH + col0 + bj * HALF;
;                     f32x4 v0 = acc[ai][bj][m][0] * r, v1 = acc[ai][bj][m][1] * r;
;                     if (seg == 0) { *(u32x4*)(U + o) = pack8(v0, v1); }
.LBB0_485:
	s_andn2_b64 vcc, exec, s[4:5]
	s_cbranch_vccnz .LBB0_487
	v_readlane_b32 s4, v254, 40
	v_readlane_b32 s5, v254, 41
	v_cvt_pk_bf16_f32 v14, v14, v15
	v_cvt_pk_bf16_f32 v15, v16, v17
	v_cvt_pk_bf16_f32 v16, v10, v11
	v_cvt_pk_bf16_f32 v17, v12, v13
	s_nop 1
	v_bfe_u32 v10, v20, 4, 6
	v_bfe_u32 v11, v20, 10, 11
	v_lshl_or_b32 v10, v10, 11, v11
	v_bfe_u32 v11, v20, 3, 1
	v_lshl_or_b32 v10, v10, 1, v11
	v_lshrrev_b32_e32 v11, 21, v20
	v_lshl_or_b32 v10, v11, 18, v10
	v_lshlrev_b32_e32 v10, 4, v10
	v_lshlrev_b32_e32 v11, 1, v20
	v_cndmask_b32_e64 v10, v10, v11, s[98:99]
	global_store_dwordx4 v10, v[14:17], s[4:5]

; __device__ __forceinline__ u32x4 pack8(const f32x4 a, const f32x4 b) { u32x4 w; w.x = cvt_pk_bf16(a[0], a[1]); w.y = cvt_pk_bf16(a[2], a[3]); w.z = cvt_pk_bf16(b[0], b[1]); w.w = cvt_pk_bf16(b[2], b[3]); return w; }
; template <class Epi, class Sched>
; __device__ __forceinline__ void gemm_phase(LAS unsigned char* lds, const Gemm g, const Sched& S, const Epi& E) {
;     ...
;         if (!has_next) break;
;     __device__ __forceinline__ void operator()(const Acc& acc, const Unit& u, int wr, int wc, int fr, int fq) const {
;     ...
; #pragma unroll
;                 for (int bj = 0; bj < 2; ++bj) {
;                     const size_t o = (size_t)row * DH + col0 + bj * HALF;
;                     f32x4 v0 = acc[ai][bj][m][0] * r, v1 = acc[ai][bj][m][1] * r;
;                     if (seg == 0) { *(u32x4*)(U + o) = pack8(v0, v1); }
.LBB0_495:
	v_readlane_b32 s4, v254, 40
	v_readlane_b32 s5, v254, 41
	v_cvt_pk_bf16_f32 v6, v6, v7
	v_cvt_pk_bf16_f32 v7, v8, v9
	v_cvt_pk_bf16_f32 v8, v2, v3
	v_cvt_pk_bf16_f32 v9, v4, v5
	s_nop 1
	v_bfe_u32 v2, v10, 4, 6
	v_bfe_u32 v3, v10, 10, 11
	v_lshl_or_b32 v2, v2, 11, v3
	v_bfe_u32 v3, v10, 3, 1
	v_lshl_or_b32 v2, v2, 1, v3
	v_lshrrev_b32_e32 v3, 21, v10
	v_lshl_or_b32 v2, v3, 18, v2
	v_lshlrev_b32_e32 v2, 4, v2
	v_lshlrev_b32_e32 v3, 1, v10
	v_cndmask_b32_e64 v2, v2, v3, s[98:99]
	global_store_dwordx4 v2, v[6:9], s[4:5]
	s_andn2_b64 vcc, exec, s[92:93]
	s_mov_b64 s[4:5], -1
	s_cbranch_vccnz .LBB0_327

; #define LAS __attribute__((address_space(3)))
; __device__ __forceinline__ void s5_prompt(const Args& a, LAS unsigned char* lds, int b, int g, int tid, int lane, int wave) {
;     ...
;     const float l16r = aux[128 + lane], l16i = aux[192 + lane];
;     {
;         const int mt = wave & 3, nt0 = (wave >> 2) * 2;
;         const bf16_t* w0 = Win + (size_t)(32 * nt0 + r32) * 256 + 8 * hh;
;         bf16x8 bw[2][16];
;         {
;             u32x4 v[8];
; #pragma unroll
;             for (int i = 0; i < 8; ++i) { const int q = tid + 512 * i, t = q >> 1, half = q & 1; v[i] = *(const u32x4*)(U + (size_t)(b * SEQ + t) * DH + 16 * g + 8 * half); }
; #pragma unroll
;             for (int ks = 0; ks < 16; ++ks) { bw[0][ks] = *(const bf16x8*)(w0 + 16 * ks); bw[1][ks] = *(const bf16x8*)(w0 + 32 * 256 + 16 * ks); }
;             asm volatile("" ::: "memory");
; #pragma unroll
;             for (int i = 0; i < 8; ++i) { const int q = tid + 512 * i, t = q >> 1, half = q & 1; *(LAS u32x4*)(XCs + (t >> 4) * S5_PITCH + (t & 15) * 32 + 16 * half) = v[i]; }
.LBB0_559:
	s_lshl_b32 s0, s35, 3
	s_and_b32 s0, s0, 56
	s_bfe_u32 s1, s35, 0x30003
	s_or_b32 s36, s0, s1
	s_lshl_b32 s0, s36, 18
	s_add_u32 s0, s13, s0
	s_addc_u32 s1, s28, 0
	s_add_u32 s6, s0, 0x10000
	s_addc_u32 s7, s1, 0
	s_lshl_b32 s37, s35, 5
	s_and_b32 s37, s37, 0xfffff800
	v_readlane_b32 s48, v254, 40
	v_readlane_b32 s49, v254, 41
	v_lshlrev_b32_e32 v34, 4, v0
	s_nop 3
	s_lshl_b32 s50, s37, 11
	s_lshl_b32 s51, s36, 16
	s_add_u32 s48, s48, s50
	s_addc_u32 s49, s49, 0
	s_add_u32 s48, s48, s51
	s_addc_u32 s49, s49, 0
	s_mul_i32 s44, s36, 0x2400
	v_or_b32_e32 v2, s37, v162
	v_or_b32_e32 v6, s37, v185
	v_or_b32_e32 v8, s37, v186
	v_or_b32_e32 v14, s37, v187
	v_or_b32_e32 v16, s37, v188
	v_or_b32_e32 v22, s37, v189
	v_or_b32_e32 v24, s37, v190
	v_lshl_add_u64 v[36:37], v[168:169], 0, s[44:45]
	s_lshl_b32 s44, s36, 5
	v_ashrrev_i32_e32 v3, 31, v2
	v_ashrrev_i32_e32 v7, 31, v6
	v_ashrrev_i32_e32 v9, 31, v8
	v_ashrrev_i32_e32 v15, 31, v14
	v_ashrrev_i32_e32 v17, 31, v16
	v_ashrrev_i32_e32 v23, 31, v22
	v_ashrrev_i32_e32 v25, 31, v24
	v_lshl_add_u64 v[30:31], v[172:173], 0, s[44:45]
	v_lshlrev_b64 v[2:3], 11, v[2:3]
	v_lshlrev_b64 v[6:7], 11, v[6:7]
	v_lshlrev_b64 v[8:9], 11, v[8:9]
	v_lshlrev_b64 v[14:15], 11, v[14:15]
	v_lshlrev_b64 v[16:17], 11, v[16:17]
	v_lshlrev_b64 v[22:23], 11, v[22:23]
	v_lshlrev_b64 v[24:25], 11, v[24:25]
	v_lshl_add_u64 v[2:3], v[30:31], 0, v[2:3]
	v_lshl_add_u64 v[6:7], v[30:31], 0, v[6:7]
	v_lshl_add_u64 v[10:11], v[30:31], 0, v[8:9]
	v_lshl_add_u64 v[14:15], v[30:31], 0, v[14:15]
	v_lshl_add_u64 v[18:19], v[30:31], 0, v[16:17]
	v_lshl_add_u64 v[22:23], v[30:31], 0, v[22:23]
	v_lshl_add_u64 v[26:27], v[30:31], 0, v[24:25]
	global_load_dwordx4 v[2:5], v34, s[48:49]
	s_nop 0
	s_add_u32 s48, s48, 0x2000
	s_addc_u32 s49, s49, 0
	global_load_dwordx4 v[6:9], v34, s[48:49]
	s_nop 0
	s_add_u32 s48, s48, 0x2000
	s_addc_u32 s49, s49, 0
	global_load_dwordx4 v[10:13], v34, s[48:49]
	s_nop 0
	s_add_u32 s48, s48, 0x2000
	s_addc_u32 s49, s49, 0
	global_load_dwordx4 v[14:17], v34, s[48:49]
	s_nop 0
	s_add_u32 s48, s48, 0x2000
	s_addc_u32 s49, s49, 0
	global_load_dwordx4 v[18:21], v34, s[48:49]
	s_nop 0
	s_add_u32 s48, s48, 0x2000
	s_addc_u32 s49, s49, 0
	global_load_dwordx4 v[22:25], v34, s[48:49]
	s_nop 0
	s_add_u32 s48, s48, 0x2000
	s_addc_u32 s49, s49, 0
	global_load_dwordx4 v[26:29], v34, s[48:49]
	v_or_b32_e32 v32, s37, v191
	v_ashrrev_i32_e32 v33, 31, v32
	v_lshlrev_b64 v[32:33], 11, v[32:33]
	v_lshl_add_u64 v[30:31], v[30:31], 0, v[32:33]
	s_add_u32 s48, s48, 0x2000
	s_addc_u32 s49, s49, 0
	global_load_dwordx4 v[30:33], v34, s[48:49]
	v_lshlrev_b32_e32 v35, 4, v210
	v_lshrrev_b32_e32 v158, 8, v0
	v_lshl_add_u32 v35, v158, 15, v35
	s_mov_b64 s[48:49], s[0:1]
	s_add_u32 s50, s0, 0x4000
	s_addc_u32 s51, s1, 0
	global_load_dwordx4 v[38:41], v35, s[48:49]
	global_load_dwordx4 v[42:45], v35, s[50:51]
	global_load_dwordx4 v[46:49], v35, s[48:49] offset:1024
	global_load_dwordx4 v[50:53], v35, s[50:51] offset:1024
	global_load_dword v34, v[36:37], off offset:512
	global_load_dword v36, v[36:37], off offset:768
	global_load_dwordx4 v[54:57], v35, s[48:49] offset:2048
	global_load_dwordx4 v[58:61], v35, s[50:51] offset:2048
	global_load_dwordx4 v[62:65], v35, s[48:49] offset:3072
	s_add_u32 s48, s48, 0x1000
	s_addc_u32 s49, s49, 0
	global_load_dwordx4 v[66:69], v35, s[48:49]
	global_load_dwordx4 v[70:73], v35, s[50:51] offset:3072
	s_add_u32 s50, s50, 0x1000
	s_addc_u32 s51, s51, 0
	global_load_dwordx4 v[74:77], v35, s[50:51]
	global_load_dwordx4 v[78:81], v35, s[48:49] offset:1024
	global_load_dwordx4 v[82:85], v35, s[48:49] offset:2048
	global_load_dwordx4 v[86:89], v35, s[50:51] offset:1024
	global_load_dwordx4 v[90:93], v35, s[50:51] offset:2048
	global_load_dwordx4 v[94:97], v35, s[48:49] offset:3072
	s_add_u32 s48, s48, 0x1000
	s_addc_u32 s49, s49, 0
	global_load_dwordx4 v[98:101], v35, s[48:49]
	global_load_dwordx4 v[102:105], v35, s[50:51] offset:3072
	s_add_u32 s50, s50, 0x1000
	s_addc_u32 s51, s51, 0
	global_load_dwordx4 v[106:109], v35, s[50:51]
	global_load_dwordx4 v[110:113], v35, s[48:49] offset:1024
	global_load_dwordx4 v[114:117], v35, s[48:49] offset:2048
	global_load_dwordx4 v[118:121], v35, s[50:51] offset:1024
	global_load_dwordx4 v[122:125], v35, s[50:51] offset:2048
	global_load_dwordx4 v[126:129], v35, s[48:49] offset:3072
	s_add_u32 s48, s48, 0x1000
	s_addc_u32 s49, s49, 0
	global_load_dwordx4 v[130:133], v35, s[48:49]
	global_load_dwordx4 v[134:137], v35, s[50:51] offset:3072
	s_add_u32 s50, s50, 0x1000
	s_addc_u32 s51, s51, 0
	global_load_dwordx4 v[138:141], v35, s[50:51]
	global_load_dwordx4 v[142:145], v35, s[48:49] offset:1024
	global_load_dwordx4 v[146:149], v35, s[48:49] offset:2048
	global_load_dwordx4 v[150:153], v35, s[50:51] offset:1024
	global_load_dwordx4 v[154:157], v35, s[50:51] offset:2048
	global_load_dwordx4 v[158:161], v35, s[48:49] offset:3072
	global_load_dwordx4 v[178:181], v35, s[50:51] offset:3072
	s_andn2_b64 vcc, exec, s[68:69]
	s_waitcnt vmcnt(41)
	ds_write_b128 v199, v[2:5]
	s_waitcnt vmcnt(40)
	ds_write_b128 v200, v[6:9]
	s_waitcnt vmcnt(39)
	ds_write_b128 v201, v[10:13]
	s_waitcnt vmcnt(38)
	ds_write_b128 v202, v[14:17]
	s_waitcnt vmcnt(37)
	ds_write_b128 v203, v[18:21]
	s_waitcnt vmcnt(36)
	ds_write_b128 v204, v[22:25]
	s_waitcnt vmcnt(35)
	ds_write_b128 v205, v[26:29]
	s_waitcnt vmcnt(34)
	ds_write_b128 v206, v[30:33]
	s_waitcnt lgkmcnt(0)
	s_barrier
; #define LAS __attribute__((address_space(3)))
; #define MFMA32(a, b, c) __builtin_amdgcn_mfma_f32_32x32x16_bf16((a), (b), (c), 0, 0, 0)
; __device__ __forceinline__ void s5_prompt(const Args& a, LAS unsigned char* lds, int b, int g, int tid, int lane, int wave) {
;     ...
;         const LAS unsigned char* xa = XCs + (32 * mt + r32) * S5_PITCH + 16 * hh;
; #pragma unroll
;         for (int ks = 0; ks < 16; ++ks) { const bf16x8 af = *(const LAS bf16x8*)(xa + 32 * ks); acc0 = MFMA32(af, bw[0][ks], acc0); acc1 = MFMA32(af, bw[1][ks], acc1); }
;         LAS float* Z = (LAS float*)ZS;
; #pragma unroll
;         for (int i = 0; i < 16; ++i) { const int j = 32 * mt + (i & 3) + 8 * (i >> 2) + 4 * hh;
;             Z[j * (S5_PITCH / 4) + 32 * nt0 + r32] = acc0[i]; Z[j * (S5_PITCH / 4) + 32 * nt0 + 32 + r32] = acc1[i]; }
;     }
;     __syncthreads();
;     bf16x8 am[24];
;     { const int mt = wave; const bf16_t* mw = MW + (size_t)(32 * mt + r32) * 384 + 8 * hh;
; #pragma unroll
;       for (int ks = 0; ks < 16; ++ks) if (ks < 2 * mt + 2) am[ks] = *(const bf16x8*)(mw + 16 * ks);
; #pragma unroll
;       for (int kq = 0; kq < 8; ++kq) am[16 + kq] = *(const bf16x8*)(mw + 256 + 16 * kq); }
	ds_read_b128 v[18:21], v207
	s_waitcnt vmcnt(33) lgkmcnt(0)
	v_mfma_f32_32x32x16_bf16 v[2:17], v[18:21], v[38:41], 0
	ds_read_b128 v[38:41], v207 offset:32
	s_waitcnt vmcnt(32)
	v_mfma_f32_32x32x16_bf16 v[18:33], v[18:21], v[42:45], 0
	s_waitcnt vmcnt(31) lgkmcnt(0)
	v_mfma_f32_32x32x16_bf16 v[2:17], v[38:41], v[46:49], v[2:17]
	s_waitcnt vmcnt(30)
	v_mfma_f32_32x32x16_bf16 v[18:33], v[38:41], v[50:53], v[18:33]
	ds_read_b128 v[38:41], v207 offset:64
	s_waitcnt vmcnt(27) lgkmcnt(0)
	v_mfma_f32_32x32x16_bf16 v[2:17], v[38:41], v[54:57], v[2:17]
	s_waitcnt vmcnt(26)
	v_mfma_f32_32x32x16_bf16 v[18:33], v[38:41], v[58:61], v[18:33]
	ds_read_b128 v[38:41], v207 offset:96
	s_waitcnt vmcnt(25) lgkmcnt(0)
	v_mfma_f32_32x32x16_bf16 v[2:17], v[38:41], v[62:65], v[2:17]
	s_waitcnt vmcnt(23)
	v_mfma_f32_32x32x16_bf16 v[18:33], v[38:41], v[70:73], v[18:33]
	ds_read_b128 v[38:41], v207 offset:128
	s_waitcnt lgkmcnt(0)
	v_mfma_f32_32x32x16_bf16 v[2:17], v[38:41], v[66:69], v[2:17]
	s_waitcnt vmcnt(22)
	v_mfma_f32_32x32x16_bf16 v[18:33], v[38:41], v[74:77], v[18:33]
	ds_read_b128 v[38:41], v207 offset:160
	s_waitcnt vmcnt(21) lgkmcnt(0)
	v_mfma_f32_32x32x16_bf16 v[2:17], v[38:41], v[78:81], v[2:17]
	s_waitcnt vmcnt(19)
	v_mfma_f32_32x32x16_bf16 v[18:33], v[38:41], v[86:89], v[18:33]
	ds_read_b128 v[38:41], v207 offset:192
	s_waitcnt lgkmcnt(0)
	v_mfma_f32_32x32x16_bf16 v[2:17], v[38:41], v[82:85], v[2:17]
	s_waitcnt vmcnt(18)
	v_mfma_f32_32x32x16_bf16 v[18:33], v[38:41], v[90:93], v[18:33]
	ds_read_b128 v[38:41], v207 offset:224
	s_waitcnt vmcnt(17) lgkmcnt(0)
	v_mfma_f32_32x32x16_bf16 v[2:17], v[38:41], v[94:97], v[2:17]
	s_waitcnt vmcnt(15)
	v_mfma_f32_32x32x16_bf16 v[18:33], v[38:41], v[102:105], v[18:33]
	ds_read_b128 v[38:41], v207 offset:256
	s_waitcnt lgkmcnt(0)
	v_mfma_f32_32x32x16_bf16 v[2:17], v[38:41], v[98:101], v[2:17]
	s_waitcnt vmcnt(14)
	v_mfma_f32_32x32x16_bf16 v[18:33], v[38:41], v[106:109], v[18:33]
	ds_read_b128 v[38:41], v207 offset:288
	s_waitcnt vmcnt(13) lgkmcnt(0)
	v_mfma_f32_32x32x16_bf16 v[2:17], v[38:41], v[110:113], v[2:17]
	s_waitcnt vmcnt(11)
	v_mfma_f32_32x32x16_bf16 v[18:33], v[38:41], v[118:121], v[18:33]
	ds_read_b128 v[38:41], v207 offset:320
	s_waitcnt lgkmcnt(0)
	v_mfma_f32_32x32x16_bf16 v[2:17], v[38:41], v[114:117], v[2:17]
	s_waitcnt vmcnt(10)
	v_mfma_f32_32x32x16_bf16 v[18:33], v[38:41], v[122:125], v[18:33]
	ds_read_b128 v[38:41], v207 offset:352
	s_waitcnt vmcnt(9) lgkmcnt(0)
	v_mfma_f32_32x32x16_bf16 v[2:17], v[38:41], v[126:129], v[2:17]
	s_waitcnt vmcnt(7)
	v_mfma_f32_32x32x16_bf16 v[18:33], v[38:41], v[134:137], v[18:33]
	ds_read_b128 v[38:41], v207 offset:384
	s_waitcnt lgkmcnt(0)
	v_mfma_f32_32x32x16_bf16 v[2:17], v[38:41], v[130:133], v[2:17]
	s_waitcnt vmcnt(6)
	v_mfma_f32_32x32x16_bf16 v[18:33], v[38:41], v[138:141], v[18:33]
	ds_read_b128 v[38:41], v207 offset:416
	s_waitcnt vmcnt(5) lgkmcnt(0)
	v_mfma_f32_32x32x16_bf16 v[2:17], v[38:41], v[142:145], v[2:17]
	s_waitcnt vmcnt(3)
	v_mfma_f32_32x32x16_bf16 v[18:33], v[38:41], v[150:153], v[18:33]
	ds_read_b128 v[38:41], v207 offset:448
	s_waitcnt lgkmcnt(0)
	v_mfma_f32_32x32x16_bf16 v[2:17], v[38:41], v[146:149], v[2:17]
	s_waitcnt vmcnt(2)
	v_mfma_f32_32x32x16_bf16 v[18:33], v[38:41], v[154:157], v[18:33]
	ds_read_b128 v[38:41], v207 offset:480
	s_waitcnt vmcnt(1) lgkmcnt(0)
	v_mfma_f32_32x32x16_bf16 v[2:17], v[38:41], v[158:161], v[2:17]
	s_waitcnt vmcnt(0)
	v_mfma_f32_32x32x16_bf16 v[18:33], v[38:41], v[178:181], v[18:33]
	s_nop 11
	ds_write2_b32 v192, v2, v18 offset1:32
	ds_write2_b32 v192, v3, v19 offset0:132 offset1:164
	ds_write2_b32 v208, v4, v20 offset0:8 offset1:40
	ds_write2_b32 v208, v5, v21 offset0:140 offset1:172
	ds_write2_b32 v209, v6, v22 offset0:32 offset1:64
	ds_write2_b32 v209, v7, v23 offset0:164 offset1:196
	ds_write2_b32 v211, v8, v24 offset0:40 offset1:72
	ds_write2_b32 v211, v9, v25 offset0:172 offset1:204
	ds_write2_b32 v212, v10, v26 offset0:64 offset1:96
	ds_write2_b32 v212, v11, v27 offset0:196 offset1:228
	v_add_u32_e32 v2, 0x2400, v192
	ds_write2_b32 v2, v12, v28 offset0:72 offset1:104
	ds_write2_b32 v2, v13, v29 offset0:204 offset1:236
	v_add_u32_e32 v2, 0x3000, v192
	ds_write2_b32 v2, v14, v30 offset0:96 offset1:128
	v_add_u32_e32 v2, 0x3200, v192
	ds_write2_b32 v2, v15, v31 offset0:100 offset1:132
	v_add_u32_e32 v2, 0x3400, v192
	ds_write2_b32 v2, v16, v32 offset0:104 offset1:136
	v_add_u32_e32 v2, 0x3600, v192
	ds_write2_b32 v2, v17, v33 offset0:108 offset1:140
	v_lshl_add_u64 v[2:3], s[6:7], 0, v[174:175]
	v_lshl_add_u64 v[2:3], v[2:3], 0, v[166:167]
	s_waitcnt lgkmcnt(0)
	s_barrier
	s_mov_b64 s[50:51], s[6:7]
	s_mul_i32 s48, s3, 0x6000
	s_add_u32 s48, s50, s48
	s_addc_u32 s49, s51, 0
	v_lshlrev_b32_e32 v225, 4, v210
	v_add_u32_e32 v226, 0x1000, v225
	v_add_u32_e32 v227, 0x2000, v225
	v_add_u32_e32 v228, 0x3000, v225
	v_add_u32_e32 v229, 0x4000, v225
	v_add_u32_e32 v230, 0x5000, v225
	global_load_dwordx4 v[66:69], v225, s[48:49]
	global_load_dwordx4 v[70:73], v225, s[48:49] offset:1024
	v_cndmask_b32_e64 v4, 0, 1, s[68:69]
	v_cmp_ne_u32_e64 s[0:1], 1, v4
	s_cbranch_vccnz .LBB0_561
	global_load_dwordx4 v[74:77], v225, s[48:49] offset:2048
	s_and_b64 vcc, exec, s[0:1]
	s_cbranch_vccnz .LBB0_563
	s_branch .LBB0_562

; __device__ __forceinline__ void s5_prompt(const Args& a, LAS unsigned char* lds, int b, int g, int tid, int lane, int wave) {
;     ...
;     { const int mt = wave; const bf16_t* mw = MW + (size_t)(32 * mt + r32) * 384 + 8 * hh;
; #pragma unroll
;       for (int ks = 0; ks < 16; ++ks) if (ks < 2 * mt + 2) am[ks] = *(const bf16x8*)(mw + 16 * ks);
; #pragma unroll
;       for (int kq = 0; kq < 8; ++kq) am[16 + kq] = *(const bf16x8*)(mw + 256 + 16 * kq); }
.LBB0_562:
	global_load_dwordx4 v[78:81], v225, s[48:49] offset:3072
.LBB0_563:
	v_cndmask_b32_e64 v4, 0, 1, s[70:71]
	v_cmp_ne_u32_e64 s[0:1], 1, v4
	s_andn2_b64 vcc, exec, s[70:71]
	s_cbranch_vccnz .LBB0_565
	global_load_dwordx4 v[82:85], v226, s[48:49]
	s_and_b64 vcc, exec, s[0:1]
	s_cbranch_vccnz .LBB0_567
	s_branch .LBB0_566

; __device__ __forceinline__ void s5_prompt(const Args& a, LAS unsigned char* lds, int b, int g, int tid, int lane, int wave) {
;     ...
;     { const int mt = wave; const bf16_t* mw = MW + (size_t)(32 * mt + r32) * 384 + 8 * hh;
; #pragma unroll
;       for (int ks = 0; ks < 16; ++ks) if (ks < 2 * mt + 2) am[ks] = *(const bf16x8*)(mw + 16 * ks);
; #pragma unroll
;       for (int kq = 0; kq < 8; ++kq) am[16 + kq] = *(const bf16x8*)(mw + 256 + 16 * kq); }
.LBB0_566:
	global_load_dwordx4 v[86:89], v226, s[48:49] offset:1024
.LBB0_567:
	v_cndmask_b32_e64 v4, 0, 1, s[72:73]
	v_cmp_ne_u32_e64 s[0:1], 1, v4
	s_andn2_b64 vcc, exec, s[72:73]
	s_cbranch_vccnz .LBB0_569
	global_load_dwordx4 v[90:93], v226, s[48:49] offset:2048
	s_and_b64 vcc, exec, s[0:1]
	s_cbranch_vccnz .LBB0_571
	s_branch .LBB0_570

; __device__ __forceinline__ void s5_prompt(const Args& a, LAS unsigned char* lds, int b, int g, int tid, int lane, int wave) {
;     ...
;     { const int mt = wave; const bf16_t* mw = MW + (size_t)(32 * mt + r32) * 384 + 8 * hh;
; #pragma unroll
;       for (int ks = 0; ks < 16; ++ks) if (ks < 2 * mt + 2) am[ks] = *(const bf16x8*)(mw + 16 * ks);
; #pragma unroll
;       for (int kq = 0; kq < 8; ++kq) am[16 + kq] = *(const bf16x8*)(mw + 256 + 16 * kq); }
.LBB0_570:
	global_load_dwordx4 v[94:97], v226, s[48:49] offset:3072
.LBB0_571:
	v_cndmask_b32_e64 v4, 0, 1, s[88:89]
	v_cmp_ne_u32_e64 s[0:1], 1, v4
	s_andn2_b64 vcc, exec, s[88:89]
	s_cbranch_vccnz .LBB0_573
	global_load_dwordx4 v[98:101], v227, s[48:49]
	s_and_b64 vcc, exec, s[0:1]
	s_cbranch_vccnz .LBB0_575
	s_branch .LBB0_574

; __device__ __forceinline__ void s5_prompt(const Args& a, LAS unsigned char* lds, int b, int g, int tid, int lane, int wave) {
;     ...
;     { const int mt = wave; const bf16_t* mw = MW + (size_t)(32 * mt + r32) * 384 + 8 * hh;
; #pragma unroll
;       for (int ks = 0; ks < 16; ++ks) if (ks < 2 * mt + 2) am[ks] = *(const bf16x8*)(mw + 16 * ks);
; #pragma unroll
;       for (int kq = 0; kq < 8; ++kq) am[16 + kq] = *(const bf16x8*)(mw + 256 + 16 * kq); }
.LBB0_574:
	global_load_dwordx4 v[102:105], v227, s[48:49] offset:1024
.LBB0_575:
	v_cndmask_b32_e64 v4, 0, 1, s[90:91]
	v_cmp_ne_u32_e64 s[0:1], 1, v4
	s_andn2_b64 vcc, exec, s[90:91]
	s_cbranch_vccnz .LBB0_577
	global_load_dwordx4 v[106:109], v227, s[48:49] offset:2048
	s_and_b64 vcc, exec, s[0:1]
	s_cbranch_vccnz .LBB0_579
	s_branch .LBB0_578

; __device__ __forceinline__ void s5_prompt(const Args& a, LAS unsigned char* lds, int b, int g, int tid, int lane, int wave) {
;     ...
;     { const int mt = wave; const bf16_t* mw = MW + (size_t)(32 * mt + r32) * 384 + 8 * hh;
; #pragma unroll
;       for (int ks = 0; ks < 16; ++ks) if (ks < 2 * mt + 2) am[ks] = *(const bf16x8*)(mw + 16 * ks);
; #pragma unroll
;       for (int kq = 0; kq < 8; ++kq) am[16 + kq] = *(const bf16x8*)(mw + 256 + 16 * kq); }
.LBB0_578:
	global_load_dwordx4 v[110:113], v227, s[48:49] offset:3072
.LBB0_579:
	v_cndmask_b32_e64 v4, 0, 1, s[92:93]
	v_cmp_ne_u32_e64 s[0:1], 1, v4
	s_andn2_b64 vcc, exec, s[92:93]
	s_cbranch_vccnz .LBB0_581
	global_load_dwordx4 v[114:117], v228, s[48:49]
	s_and_b64 vcc, exec, s[0:1]
	s_cbranch_vccnz .LBB0_583
	s_branch .LBB0_582

; __device__ __forceinline__ void s5_prompt(const Args& a, LAS unsigned char* lds, int b, int g, int tid, int lane, int wave) {
;     ...
;     { const int mt = wave; const bf16_t* mw = MW + (size_t)(32 * mt + r32) * 384 + 8 * hh;
; #pragma unroll
;       for (int ks = 0; ks < 16; ++ks) if (ks < 2 * mt + 2) am[ks] = *(const bf16x8*)(mw + 16 * ks);
; #pragma unroll
;       for (int kq = 0; kq < 8; ++kq) am[16 + kq] = *(const bf16x8*)(mw + 256 + 16 * kq); }
.LBB0_582:
	global_load_dwordx4 v[118:121], v228, s[48:49] offset:1024
.LBB0_583:
	v_cndmask_b32_e64 v4, 0, 1, s[94:95]
	v_cmp_ne_u32_e64 s[0:1], 1, v4
	s_andn2_b64 vcc, exec, s[94:95]
	s_cbranch_vccnz .LBB0_585
	global_load_dwordx4 v[122:125], v228, s[48:49] offset:2048
	s_and_b64 vcc, exec, s[0:1]
	s_cbranch_vccz .LBB0_586
	s_branch .LBB0_587

; #define LAS __attribute__((address_space(3)))
; __device__ __forceinline__ void s5_prompt(const Args& a, LAS unsigned char* lds, int b, int g, int tid, int lane, int wave) {
;     ...
;     { const int mt = wave; const bf16_t* mw = MW + (size_t)(32 * mt + r32) * 384 + 8 * hh;
; #pragma unroll
;       for (int ks = 0; ks < 16; ++ks) if (ks < 2 * mt + 2) am[ks] = *(const bf16x8*)(mw + 16 * ks);
; #pragma unroll
;       for (int kq = 0; kq < 8; ++kq) am[16 + kq] = *(const bf16x8*)(mw + 256 + 16 * kq); }
;     if (wave == 0) {
;         const LAS float* zp = (const LAS float*)ZS + lane;
;         LAS unsigned short* sp = (LAS unsigned short*)ZS + lane;
;         float sr = 0.f, si = 0.f;
; #pragma unroll 1
;         for (int jb = 0; jb < 16; ++jb) {
;             asm volatile("" : "+v"(zp), "+v"(sp));
;             float zr[8], zi[8];
; #pragma unroll
;             for (int i = 0; i < 8; ++i) { zr[i] = zp[i * (S5_PITCH / 4)]; zi[i] = zp[i * (S5_PITCH / 4) + 64]; }
.LBB0_586:
	global_load_dwordx4 v[126:129], v228, s[48:49] offset:3072
.LBB0_587:
	global_load_dwordx4 v[130:133], v229, s[48:49]
	global_load_dwordx4 v[134:137], v229, s[48:49] offset:1024
	global_load_dwordx4 v[138:141], v229, s[48:49] offset:2048
	global_load_dwordx4 v[142:145], v229, s[48:49] offset:3072
	global_load_dwordx4 v[146:149], v230, s[48:49]
	global_load_dwordx4 v[150:153], v230, s[48:49] offset:1024
	global_load_dwordx4 v[154:157], v230, s[48:49] offset:2048
	global_load_dwordx4 v[158:161], v230, s[48:49] offset:3072
	v_cndmask_b32_e64 v2, 0, 1, s[18:19]
	v_cmp_ne_u32_e64 s[0:1], 1, v2
	s_andn2_b64 vcc, exec, s[18:19]
	s_cbranch_vccnz .LBB0_591
	v_mov_b32_e32 v2, 0
	v_mov_b32_e32 v35, v34
	v_mov_b32_e32 v37, v36
	s_mov_b32 s38, 16
	v_mov_b32_e32 v4, v193
	v_mov_b32_e32 v5, v194
	v_mov_b32_e32 v3, v2

; __device__ __forceinline__ void s5_prompt(const Args& a, LAS unsigned char* lds, int b, int g, int tid, int lane, int wave) {
;     ...
; #pragma unroll 1
;     for (int pass = 0; pass < 2; ++pass) {
;         const int mt = pass ? 7 - wave : wave, n0 = 2 * pass;
;         const int nks = 2 * mt + 2;
;         const bf16_t* mw = MW + (size_t)(32 * mt + r32) * 384 + 8 * hh;
;         if (pass == 1) {
; #pragma unroll
;             for (int ks = 0; ks < 16; ++ks) if (ks < nks) am[ks] = *(const bf16x8*)(mw + 16 * ks);
; #pragma unroll
;             for (int kq = 0; kq < 8; ++kq) am[16 + kq] = *(const bf16x8*)(mw + 256 + 16 * kq);
;         }
.LBB0_596:
	s_andn2_b64 vcc, exec, s[6:7]
	s_cbranch_vccnz .LBB0_630
	s_mul_i32 s48, s78, 0x6000
	s_add_u32 s48, s50, s48
	s_addc_u32 s49, s51, 0
	v_lshl_or_b32 v2, s78, 5, v184
	v_mad_i64_i32 v[2:3], s[6:7], v2, s33, v[178:179]
	v_cndmask_b32_e64 v4, 0, 1, s[96:97]
	v_cmp_ne_u32_e64 s[6:7], 1, v4
	s_andn2_b64 vcc, exec, s[96:97]
	s_cbranch_vccnz .LBB0_613
	global_load_dwordx4 v[66:69], v225, s[48:49]
	s_and_b64 vcc, exec, s[6:7]
	s_cbranch_vccz .LBB0_614

; __device__ __forceinline__ void s5_prompt(const Args& a, LAS unsigned char* lds, int b, int g, int tid, int lane, int wave) {
;     ...
;         if (pass == 1) {
; #pragma unroll
;             for (int ks = 0; ks < 16; ++ks) if (ks < nks) am[ks] = *(const bf16x8*)(mw + 16 * ks);
; #pragma unroll
;             for (int kq = 0; kq < 8; ++kq) am[16 + kq] = *(const bf16x8*)(mw + 256 + 16 * kq);
;         }
.LBB0_600:
	global_load_dwordx4 v[74:77], v225, s[48:49] offset:2048
	s_and_b64 vcc, exec, s[6:7]
	s_cbranch_vccz .LBB0_616

; __device__ __forceinline__ void s5_prompt(const Args& a, LAS unsigned char* lds, int b, int g, int tid, int lane, int wave) {
;     ...
;         if (pass == 1) {
; #pragma unroll
;             for (int ks = 0; ks < 16; ++ks) if (ks < nks) am[ks] = *(const bf16x8*)(mw + 16 * ks);
; #pragma unroll
;             for (int kq = 0; kq < 8; ++kq) am[16 + kq] = *(const bf16x8*)(mw + 256 + 16 * kq);
;         }
.LBB0_602:
	global_load_dwordx4 v[82:85], v226, s[48:49]
	s_and_b64 vcc, exec, s[6:7]
	s_cbranch_vccz .LBB0_618

; __device__ __forceinline__ void s5_prompt(const Args& a, LAS unsigned char* lds, int b, int g, int tid, int lane, int wave) {
;     ...
;         if (pass == 1) {
; #pragma unroll
;             for (int ks = 0; ks < 16; ++ks) if (ks < nks) am[ks] = *(const bf16x8*)(mw + 16 * ks);
; #pragma unroll
;             for (int kq = 0; kq < 8; ++kq) am[16 + kq] = *(const bf16x8*)(mw + 256 + 16 * kq);
;         }
.LBB0_604:
	global_load_dwordx4 v[90:93], v226, s[48:49] offset:2048
	s_and_b64 vcc, exec, s[6:7]
	s_cbranch_vccz .LBB0_620

; __device__ __forceinline__ void s5_prompt(const Args& a, LAS unsigned char* lds, int b, int g, int tid, int lane, int wave) {
;     ...
;         if (pass == 1) {
; #pragma unroll
;             for (int ks = 0; ks < 16; ++ks) if (ks < nks) am[ks] = *(const bf16x8*)(mw + 16 * ks);
; #pragma unroll
;             for (int kq = 0; kq < 8; ++kq) am[16 + kq] = *(const bf16x8*)(mw + 256 + 16 * kq);
;         }
.LBB0_606:
	global_load_dwordx4 v[98:101], v227, s[48:49]
	s_and_b64 vcc, exec, s[6:7]
	s_cbranch_vccz .LBB0_622

; __device__ __forceinline__ void s5_prompt(const Args& a, LAS unsigned char* lds, int b, int g, int tid, int lane, int wave) {
;     ...
;         if (pass == 1) {
; #pragma unroll
;             for (int ks = 0; ks < 16; ++ks) if (ks < nks) am[ks] = *(const bf16x8*)(mw + 16 * ks);
; #pragma unroll
;             for (int kq = 0; kq < 8; ++kq) am[16 + kq] = *(const bf16x8*)(mw + 256 + 16 * kq);
;         }
.LBB0_608:
	global_load_dwordx4 v[106:109], v227, s[48:49] offset:2048
	s_and_b64 vcc, exec, s[6:7]
	s_cbranch_vccz .LBB0_624

; __device__ __forceinline__ void s5_prompt(const Args& a, LAS unsigned char* lds, int b, int g, int tid, int lane, int wave) {
;     ...
;         if (pass == 1) {
; #pragma unroll
;             for (int ks = 0; ks < 16; ++ks) if (ks < nks) am[ks] = *(const bf16x8*)(mw + 16 * ks);
; #pragma unroll
;             for (int kq = 0; kq < 8; ++kq) am[16 + kq] = *(const bf16x8*)(mw + 256 + 16 * kq);
;         }
.LBB0_610:
	global_load_dwordx4 v[114:117], v228, s[48:49]
	s_and_b64 vcc, exec, s[6:7]
	s_cbranch_vccz .LBB0_626

; __device__ __forceinline__ void s5_prompt(const Args& a, LAS unsigned char* lds, int b, int g, int tid, int lane, int wave) {
;     ...
;         if (pass == 1) {
; #pragma unroll
;             for (int ks = 0; ks < 16; ++ks) if (ks < nks) am[ks] = *(const bf16x8*)(mw + 16 * ks);
; #pragma unroll
;             for (int kq = 0; kq < 8; ++kq) am[16 + kq] = *(const bf16x8*)(mw + 256 + 16 * kq);
;         }
.LBB0_612:
	global_load_dwordx4 v[122:125], v228, s[48:49] offset:2048
	s_and_b64 vcc, exec, s[0:1]
	s_cbranch_vccz .LBB0_628
	s_branch .LBB0_629

; __device__ __forceinline__ void s5_prompt(const Args& a, LAS unsigned char* lds, int b, int g, int tid, int lane, int wave) {
;     ...
;         if (pass == 1) {
; #pragma unroll
;             for (int ks = 0; ks < 16; ++ks) if (ks < nks) am[ks] = *(const bf16x8*)(mw + 16 * ks);
; #pragma unroll
;             for (int kq = 0; kq < 8; ++kq) am[16 + kq] = *(const bf16x8*)(mw + 256 + 16 * kq);
;         }
.LBB0_614:
	global_load_dwordx4 v[70:73], v225, s[48:49] offset:1024
	v_cndmask_b32_e64 v4, 0, 1, s[86:87]
	v_cmp_ne_u32_e64 s[6:7], 1, v4
	s_andn2_b64 vcc, exec, s[86:87]
	s_cbranch_vccz .LBB0_600

; __device__ __forceinline__ void s5_prompt(const Args& a, LAS unsigned char* lds, int b, int g, int tid, int lane, int wave) {
;     ...
;         if (pass == 1) {
; #pragma unroll
;             for (int ks = 0; ks < 16; ++ks) if (ks < nks) am[ks] = *(const bf16x8*)(mw + 16 * ks);
; #pragma unroll
;             for (int kq = 0; kq < 8; ++kq) am[16 + kq] = *(const bf16x8*)(mw + 256 + 16 * kq);
;         }
.LBB0_616:
	global_load_dwordx4 v[78:81], v225, s[48:49] offset:3072
	v_cndmask_b32_e64 v4, 0, 1, s[84:85]
	v_cmp_ne_u32_e64 s[6:7], 1, v4
	s_andn2_b64 vcc, exec, s[84:85]
	s_cbranch_vccz .LBB0_602

; __device__ __forceinline__ void s5_prompt(const Args& a, LAS unsigned char* lds, int b, int g, int tid, int lane, int wave) {
;     ...
;         if (pass == 1) {
; #pragma unroll
;             for (int ks = 0; ks < 16; ++ks) if (ks < nks) am[ks] = *(const bf16x8*)(mw + 16 * ks);
; #pragma unroll
;             for (int kq = 0; kq < 8; ++kq) am[16 + kq] = *(const bf16x8*)(mw + 256 + 16 * kq);
;         }
.LBB0_618:
	global_load_dwordx4 v[86:89], v226, s[48:49] offset:1024
	v_cndmask_b32_e64 v4, 0, 1, s[4:5]
	v_cmp_ne_u32_e64 s[6:7], 1, v4
	s_andn2_b64 vcc, exec, s[4:5]
	s_cbranch_vccz .LBB0_604

; __device__ __forceinline__ void s5_prompt(const Args& a, LAS unsigned char* lds, int b, int g, int tid, int lane, int wave) {
;     ...
;         if (pass == 1) {
; #pragma unroll
;             for (int ks = 0; ks < 16; ++ks) if (ks < nks) am[ks] = *(const bf16x8*)(mw + 16 * ks);
; #pragma unroll
;             for (int kq = 0; kq < 8; ++kq) am[16 + kq] = *(const bf16x8*)(mw + 256 + 16 * kq);
;         }
.LBB0_620:
	global_load_dwordx4 v[94:97], v226, s[48:49] offset:3072
	v_cndmask_b32_e64 v4, 0, 1, s[82:83]
	v_cmp_ne_u32_e64 s[6:7], 1, v4
	s_andn2_b64 vcc, exec, s[82:83]
	s_cbranch_vccz .LBB0_606

; __device__ __forceinline__ void s5_prompt(const Args& a, LAS unsigned char* lds, int b, int g, int tid, int lane, int wave) {
;     ...
;         if (pass == 1) {
; #pragma unroll
;             for (int ks = 0; ks < 16; ++ks) if (ks < nks) am[ks] = *(const bf16x8*)(mw + 16 * ks);
; #pragma unroll
;             for (int kq = 0; kq < 8; ++kq) am[16 + kq] = *(const bf16x8*)(mw + 256 + 16 * kq);
;         }
.LBB0_622:
	global_load_dwordx4 v[102:105], v227, s[48:49] offset:1024
	v_cndmask_b32_e64 v4, 0, 1, s[30:31]
	v_cmp_ne_u32_e64 s[6:7], 1, v4
	s_andn2_b64 vcc, exec, s[30:31]
	s_cbranch_vccz .LBB0_608

; __device__ __forceinline__ void s5_prompt(const Args& a, LAS unsigned char* lds, int b, int g, int tid, int lane, int wave) {
;     ...
;         if (pass == 1) {
; #pragma unroll
;             for (int ks = 0; ks < 16; ++ks) if (ks < nks) am[ks] = *(const bf16x8*)(mw + 16 * ks);
; #pragma unroll
;             for (int kq = 0; kq < 8; ++kq) am[16 + kq] = *(const bf16x8*)(mw + 256 + 16 * kq);
;         }
.LBB0_624:
	global_load_dwordx4 v[110:113], v227, s[48:49] offset:3072
	v_cndmask_b32_e64 v4, 0, 1, s[74:75]
	v_cmp_ne_u32_e64 s[6:7], 1, v4
	s_andn2_b64 vcc, exec, s[74:75]
	s_cbranch_vccz .LBB0_610

; __device__ __forceinline__ void s5_prompt(const Args& a, LAS unsigned char* lds, int b, int g, int tid, int lane, int wave) {
;     ...
;         if (pass == 1) {
; #pragma unroll
;             for (int ks = 0; ks < 16; ++ks) if (ks < nks) am[ks] = *(const bf16x8*)(mw + 16 * ks);
; #pragma unroll
;             for (int kq = 0; kq < 8; ++kq) am[16 + kq] = *(const bf16x8*)(mw + 256 + 16 * kq);
;         }
.LBB0_626:
	global_load_dwordx4 v[118:121], v228, s[48:49] offset:1024
	s_and_b64 vcc, exec, s[0:1]
	s_cbranch_vccz .LBB0_612

; __device__ __forceinline__ void s5_prompt(const Args& a, LAS unsigned char* lds, int b, int g, int tid, int lane, int wave) {
;     ...
;             for (int ks = 0; ks < 16; ++ks) if (ks < nks) am[ks] = *(const bf16x8*)(mw + 16 * ks);
; #pragma unroll
;             for (int kq = 0; kq < 8; ++kq) am[16 + kq] = *(const bf16x8*)(mw + 256 + 16 * kq);
;         }
.LBB0_629:
	global_load_dwordx4 v[130:133], v229, s[48:49]
	global_load_dwordx4 v[134:137], v229, s[48:49] offset:1024
	global_load_dwordx4 v[138:141], v229, s[48:49] offset:2048
	global_load_dwordx4 v[142:145], v229, s[48:49] offset:3072
	global_load_dwordx4 v[146:149], v230, s[48:49]
	global_load_dwordx4 v[150:153], v230, s[48:49] offset:1024
	global_load_dwordx4 v[154:157], v230, s[48:49] offset:2048
	global_load_dwordx4 v[158:161], v230, s[48:49] offset:3072
